# attention phase start: rpb max with 8 loads in flight per thread (was 2 per full drain plus remainder loop)
# speedup vs baseline: 1.0034x; 1.0034x over previous
; DI int otid() { int t = threadIdx.x; asm volatile("" : "+v"(t)); return t; }
; DI void phase_attn(const Params& p, int l, bool last, char* smem) {
;     ...
;     const int tid = otid();
;     float a = 0.f, b2 = 0.f, c = 0.f, d = 0.f, e = 0.f;
;     if (tid < 96) { a = fabsf(p.g_mla_q[l * 96 + tid]); b2 = fabsf(p.g_mla_k[l * 96 + tid]); }
;     if (tid < 64) { c = fabsf(p.g_na_q[l * 64 + tid]); d = fabsf(p.g_na_k[l * 64 + tid]); }
;     for (int i = tid; i < 8 * 465; i += 512) e = fmaxf(e, p.rpb[(size_t)l * 8 * 465 + i]);
; #pragma unroll
;     for (int o = 32; o >= 1; o >>= 1) { a = fmaxf(a, __shfl_xor(a, o)); b2 = fmaxf(b2, __shfl_xor(b2, o)); c = fmaxf(c, __shfl_xor(c, o)); d = fmaxf(d, __shfl_xor(d, o)); e = fmaxf(e, __shfl_xor(e, o)); }
.LBB0_978:
	s_or_b64 exec, exec, s[0:1]
	v_readlane_b32 s18, v254, 35
	v_readlane_b32 s19, v254, 36
	s_movk_i32 s26, 0xe87
	v_mov_b32_e32 v20, v2
	v_min_u32_e32 v20, s26, v20
	v_lshlrev_b32_e32 v20, 2, v20
	v_add_u32_e32 v21, 0x200, v2
	v_min_u32_e32 v21, s26, v21
	v_lshlrev_b32_e32 v21, 2, v21
	v_add_u32_e32 v22, 0x400, v2
	v_min_u32_e32 v22, s26, v22
	v_lshlrev_b32_e32 v22, 2, v22
	v_add_u32_e32 v23, 0x600, v2
	v_min_u32_e32 v23, s26, v23
	v_lshlrev_b32_e32 v23, 2, v23
	v_add_u32_e32 v24, 0x800, v2
	v_min_u32_e32 v24, s26, v24
	v_lshlrev_b32_e32 v24, 2, v24
	v_add_u32_e32 v25, 0xa00, v2
	v_min_u32_e32 v25, s26, v25
	v_lshlrev_b32_e32 v25, 2, v25
	v_add_u32_e32 v26, 0xc00, v2
	v_min_u32_e32 v26, s26, v26
	v_lshlrev_b32_e32 v26, 2, v26
	v_add_u32_e32 v27, 0xe00, v2
	v_min_u32_e32 v27, s26, v27
	v_lshlrev_b32_e32 v27, 2, v27
	global_load_dword v30, v20, s[18:19]
	global_load_dword v31, v21, s[18:19]
	global_load_dword v32, v22, s[18:19]
	global_load_dword v33, v23, s[18:19]
	global_load_dword v34, v24, s[18:19]
	global_load_dword v35, v25, s[18:19]
	global_load_dword v36, v26, s[18:19]
	global_load_dword v37, v27, s[18:19]
	v_mov_b32_e32 v3, 0
	s_waitcnt vmcnt(0)
	v_max_f32_e32 v30, v30, v30
	v_max_f32_e32 v3, v3, v30
	v_max_f32_e32 v31, v31, v31
	v_max_f32_e32 v3, v3, v31
	v_max_f32_e32 v32, v32, v32
	v_max_f32_e32 v3, v3, v32
	v_max_f32_e32 v33, v33, v33
	v_max_f32_e32 v3, v3, v33
	v_max_f32_e32 v34, v34, v34
	v_max_f32_e32 v3, v3, v34
	v_max_f32_e32 v35, v35, v35
	v_max_f32_e32 v3, v3, v35
	v_max_f32_e32 v36, v36, v36
	v_max_f32_e32 v3, v3, v36
	v_max_f32_e32 v37, v37, v37
	v_max_f32_e32 v3, v3, v37
